# NSA 64-key tile: packed subtract of running max, packed-tree row sum, bias/scale fma pairs pipelined over two temporaries (no padding nops)
# baseline (speedup 1.0000x reference)
; DEV f32x16 mfma32(bf16x8 a, bf16x8 b, f32x16 c) { return __builtin_amdgcn_mfma_f32_32x32x16_bf16(a, b, c, 0, 0, 0); }
; DEV void att_tile64(AttAcc& A, const f32x16& s0, const f32x16& s1, float qs, float slope2, int dt, float lane_bias, bool masked, int wlim,
;                     const bf16_t* vt, size_t vstride) {
;     ...
;   for (int i = 0; i < 32; ++i) { p[i] = __builtin_amdgcn_exp2f(sc[i] - A.m); ps += p[i]; }
;   A.l += ps;
; __device__ void nsa_item(const Params& P, int l, int item, char* smem) {
;     ...
;       for (int i = 0; i < ntile; ++i) {
;         const int kb = khi - 64 * i;
;         const bool more = (i + 1 < ntile);
;         if (more) {
;           rk0 = *(const uint4*)(kgp + (size_t)(kb - 64) * HS); rk1 = *(const uint4*)(kgp + (size_t)(kb - 32) * HS);
;           rv0 = *(const uint4*)(vgp + kb - 64); rv1 = *(const uint4*)(vgp + (size_t)32 * 4096 + kb - 64);
;         }
;         const bf16_t* buf = kvs + (i & 1) * 9216;
;         f32x16 s0, s1;
; #pragma unroll
;         for (int e = 0; e < 16; ++e) { s0[e] = 0.f; s1[e] = 0.f; }
;         {
;           const bf16_t* kl = buf + q * 72 + hk * 8;
; #pragma unroll
;           for (int ks = 0; ks < 4; ++ks) {
;             s0 = mfma32(*(const bf16x8*)(kl + ks * 16), qf[ks], s0);
;             s1 = mfma32(*(const bf16x8*)(kl + 32 * 72 + ks * 16), qf[ks], s1);
;           }
;         }
;         float lane_bias = 0.f;
;         if (br == 0) { const bool selj = (selmask >> (kb >> 6)) & 1ull; lane_bias = selj ? 0.f : 1e30f; }
;         const bool masked = (kb + 63 > t0) || (br == 1 && kb <= t0 - 481);
;         att_tile64(A, s0, s1, qs2, slope2, t - kb - 8 * hk, lane_bias, masked, wlim, buf + 4608 + q * 72 + 8 * hk, 72);
;         if (more) {
;           bf16_t* nb = kvs + ((i + 1) & 1) * 9216;
;           *(uint4*)(nb + koff) = rk0; *(uint4*)(nb + koff + 32 * 72) = rk1;
;           *(uint4*)(nb + voff) = rv0; *(uint4*)(nb + voff + 32 * 72) = rv1;
;         }
;         __syncthreads();
.LBB0_181:
	v_pk_add_f32 v[46:47], v[46:47], v[60:61]
	v_pk_add_f32 v[52:53], v[52:53], v[54:55]
	v_pk_add_f32 v[56:57], v[56:57], v[58:59]
	v_pk_add_f32 v[42:43], v[42:43], v[44:45]
	v_pk_add_f32 v[62:63], v[62:63], v[50:51]
	v_pk_add_f32 v[48:49], v[48:49], v[34:35]
	v_pk_add_f32 v[36:37], v[36:37], v[38:39]
	v_pk_add_f32 v[40:41], v[40:41], v[32:33]
	v_pk_add_f32 v[46:47], v[46:47], v[52:53]
	v_pk_add_f32 v[56:57], v[56:57], v[42:43]
	v_pk_add_f32 v[62:63], v[62:63], v[48:49]
	v_pk_add_f32 v[36:37], v[36:37], v[40:41]
	v_pk_add_f32 v[46:47], v[46:47], v[56:57]
	v_pk_add_f32 v[62:63], v[62:63], v[36:37]
	v_pk_add_f32 v[46:47], v[46:47], v[62:63]
	v_add_f32_e32 v46, v46, v47
	v_add_f32_e32 v156, v156, v46
	v_readlane_b32 s46, v253, 0
	v_readlane_b32 s47, v253, 1
	v_readlane_b32 s48, v253, 2
	s_lshl_b32 s49, s48, 6
	s_add_i32 s49, s49, 63
	s_sub_i32 s39, s63, s49
	s_mov_b32 s63, s49
	v_add_u32_e32 v157, s39, v157
	s_flbit_i32_b64 s39, s[46:47]
	s_sub_i32 s39, 63, s39
	s_cmp_lg_u64 s[46:47], 0
	s_cselect_b32 s39, s39, s48
	s_bitset0_b64 s[46:47], s39
	s_sub_i32 s49, s48, s39
	v_writelane_b32 v253, s46, 0
	s_nop 1
	v_writelane_b32 v253, s47, 1
	v_writelane_b32 v253, s39, 2
	s_mul_i32 s46, s49, 0xfffbf400
	s_ashr_i32 s47, s46, 31
	v_lshl_add_u64 v[114:115], v[114:115], 0, s[46:47]
	s_lshl_b32 s46, s49, 7
	s_sub_i32 s46, 0, s46
	s_ashr_i32 s47, s46, 31
	v_lshl_add_u64 v[112:113], v[112:113], 0, s[46:47]
	s_cmp_eq_u32 s62, s2
	s_waitcnt lgkmcnt(0)
	s_barrier
	s_cbranch_scc1 .LBB0_190

; DEV f32x16 mfma32(bf16x8 a, bf16x8 b, f32x16 c) { return __builtin_amdgcn_mfma_f32_32x32x16_bf16(a, b, c, 0, 0, 0); }
; DEV void att_tile64(AttAcc& A, const f32x16& s0, const f32x16& s1, float qs, float slope2, int dt, float lane_bias, bool masked, int wlim,
;                     const bf16_t* vt, size_t vstride) {
;   const float sb = slope2 * (float)dt + lane_bias;
;   float sc[32];
; #pragma unroll
;   for (int i = 0; i < 16; ++i) {
;     const int c = (i & 7) + 16 * (i >> 3);
;     sc[i] = fmaf(s0[i], qs, fmaf(slope2, (float)c, -sb));
;     sc[16 + i] = fmaf(s1[i], qs, fmaf(slope2, (float)(c + 32), -sb));
;   }
; __device__ void nsa_item(const Params& P, int l, int item, char* smem) {
;     ...
; #pragma unroll
;         for (int e = 0; e < 16; ++e) { s0[e] = 0.f; s1[e] = 0.f; }
;         {
;           const bf16_t* kl = buf + q * 72 + hk * 8;
; #pragma unroll
;           for (int ks = 0; ks < 4; ++ks) {
;             s0 = mfma32(*(const bf16x8*)(kl + ks * 16), qf[ks], s0);
;             s1 = mfma32(*(const bf16x8*)(kl + 32 * 72 + ks * 16), qf[ks], s1);
;           }
;         }
;         float lane_bias = 0.f;
;         if (br == 0) { const bool selj = (selmask >> (kb >> 6)) & 1ull; lane_bias = selj ? 0.f : 1e30f; }
;         const bool masked = (kb + 63 > t0) || (br == 1 && kb <= t0 - 481);
;         att_tile64(A, s0, s1, qs2, slope2, t - kb - 8 * hk, lane_bias, masked, wlim, buf + 4608 + q * 72 + 8 * hk, 72);
.LBB0_184:
	s_sub_i32 s39, s63, 63
	s_bitcmp1_b32 s2, 0
	s_cselect_b32 s48, 0x4800, 0
	v_add_u32_e32 v159, s48, v153
	ds_read_b128 v[32:35], v159 offset:34816
	ds_read_b128 v[116:119], v159 offset:34848
	s_ashr_i32 s48, s39, 6
	s_lshl_b64 s[48:49], 1, s48
	s_waitcnt lgkmcnt(1)
	v_mfma_f32_32x32x16_bf16 v[48:63], v[32:35], v[64:67], 0
	ds_read_b128 v[32:35], v159 offset:39424
	s_waitcnt lgkmcnt(1)
	v_mfma_f32_32x32x16_bf16 v[48:63], v[116:119], v[68:71], v[48:63]
	ds_read_b128 v[116:119], v159 offset:39456
	s_waitcnt lgkmcnt(1)
	v_mfma_f32_32x32x16_bf16 v[32:47], v[32:35], v[64:67], 0
	s_waitcnt lgkmcnt(0)
	v_mfma_f32_32x32x16_bf16 v[32:47], v[116:119], v[68:71], v[32:47]
	ds_read_b128 v[116:119], v159 offset:34880
	s_waitcnt lgkmcnt(0)
	v_mfma_f32_32x32x16_bf16 v[48:63], v[116:119], v[72:75], v[48:63]
	ds_read_b128 v[116:119], v159 offset:39488
	s_waitcnt lgkmcnt(0)
	v_mfma_f32_32x32x16_bf16 v[32:47], v[116:119], v[72:75], v[32:47]
	ds_read_b128 v[116:119], v159 offset:34912
	s_waitcnt lgkmcnt(0)
	v_mfma_f32_32x32x16_bf16 v[48:63], v[116:119], v[76:79], v[48:63]
	ds_read_b128 v[116:119], v159 offset:39520
	s_waitcnt lgkmcnt(0)
	v_mfma_f32_32x32x16_bf16 v[32:47], v[116:119], v[76:79], v[32:47]
	v_and_b32_e32 v117, s49, v97
	v_and_b32_e32 v116, s48, v96
	v_cmp_eq_u64_e32 vcc, 0, v[116:117]
	v_cvt_f32_i32_e32 v116, v157
	s_and_b64 vcc, s[42:43], vcc
	v_cndmask_b32_e32 v160, 0, v218, vcc
	s_cmp_gt_i32 s63, s50
	v_fmac_f32_e32 v160, v100, v116
	v_fma_f32 v116, v100, 0, -v160
	v_sub_f32_e32 v117, v100, v160
	v_pk_fma_f32 v[118:119], v[48:49], s[36:37], v[116:117] op_sel_hi:[1,0,1]
	v_pk_fma_f32 v[48:49], v[100:101], s[34:35], v[160:161] op_sel_hi:[1,1,0] neg_lo:[0,0,1] neg_hi:[0,0,1]
	s_cselect_b64 s[48:49], -1, 0
	v_pk_fma_f32 v[116:117], v[32:33], s[36:37], v[48:49] op_sel_hi:[1,0,1]
	v_pk_fma_f32 v[32:33], v[100:101], s[12:13], v[160:161] op_sel_hi:[1,1,0] neg_lo:[0,0,1] neg_hi:[0,0,1]
	s_cmp_le_i32 s39, s65
	v_pk_fma_f32 v[120:121], v[50:51], s[36:37], v[32:33] op_sel_hi:[1,0,1]
	v_pk_fma_f32 v[32:33], v[100:101], s[8:9], v[160:161] op_sel_hi:[1,1,0] neg_lo:[0,0,1] neg_hi:[0,0,1]
	s_cselect_b64 vcc, -1, 0
	v_pk_fma_f32 v[50:51], v[34:35], s[36:37], v[32:33] op_sel_hi:[1,0,1]
	v_pk_fma_f32 v[32:33], v[100:101], s[10:11], v[160:161] op_sel_hi:[1,1,0] neg_lo:[0,0,1] neg_hi:[0,0,1]
	s_and_b64 vcc, s[44:45], vcc
	v_pk_fma_f32 v[52:53], v[52:53], s[36:37], v[32:33] op_sel_hi:[1,0,1]
	v_pk_fma_f32 v[32:33], v[100:101], s[14:15], v[160:161] op_sel_hi:[1,1,0] neg_lo:[0,0,1] neg_hi:[0,0,1]
	s_or_b64 s[48:49], s[48:49], vcc
	v_pk_fma_f32 v[48:49], v[36:37], s[36:37], v[32:33] op_sel_hi:[1,0,1]
	v_pk_fma_f32 v[32:33], v[100:101], s[16:17], v[160:161] op_sel_hi:[1,1,0] neg_lo:[0,0,1] neg_hi:[0,0,1]
	s_andn2_b64 vcc, exec, s[48:49]
	v_pk_fma_f32 v[54:55], v[54:55], s[36:37], v[32:33] op_sel_hi:[1,0,1]
	v_pk_fma_f32 v[32:33], v[100:101], s[18:19], v[160:161] op_sel_hi:[1,1,0] neg_lo:[0,0,1] neg_hi:[0,0,1]
	v_pk_fma_f32 v[162:163], v[100:101], s[20:21], v[160:161] op_sel_hi:[1,1,0] neg_lo:[0,0,1] neg_hi:[0,0,1]
	v_pk_fma_f32 v[34:35], v[38:39], s[36:37], v[32:33] op_sel_hi:[1,0,1]
	v_pk_fma_f32 v[32:33], v[100:101], s[22:23], v[160:161] op_sel_hi:[1,1,0] neg_lo:[0,0,1] neg_hi:[0,0,1]
	v_pk_fma_f32 v[56:57], v[56:57], s[36:37], v[162:163] op_sel_hi:[1,0,1]
	v_pk_fma_f32 v[162:163], v[100:101], s[84:85], v[160:161] op_sel_hi:[1,1,0] neg_lo:[0,0,1] neg_hi:[0,0,1]
	v_pk_fma_f32 v[36:37], v[40:41], s[36:37], v[32:33] op_sel_hi:[1,0,1]
	v_pk_fma_f32 v[32:33], v[100:101], s[86:87], v[160:161] op_sel_hi:[1,1,0] neg_lo:[0,0,1] neg_hi:[0,0,1]
	v_pk_fma_f32 v[58:59], v[58:59], s[36:37], v[162:163] op_sel_hi:[1,0,1]
	v_pk_fma_f32 v[162:163], v[100:101], s[88:89], v[160:161] op_sel_hi:[1,1,0] neg_lo:[0,0,1] neg_hi:[0,0,1]
	v_pk_fma_f32 v[38:39], v[42:43], s[36:37], v[32:33] op_sel_hi:[1,0,1]
	v_pk_fma_f32 v[32:33], v[100:101], s[90:91], v[160:161] op_sel_hi:[1,1,0] neg_lo:[0,0,1] neg_hi:[0,0,1]
	v_pk_fma_f32 v[42:43], v[60:61], s[36:37], v[162:163] op_sel_hi:[1,0,1]
	v_pk_fma_f32 v[162:163], v[100:101], s[92:93], v[160:161] op_sel_hi:[1,1,0] neg_lo:[0,0,1] neg_hi:[0,0,1]
	v_pk_fma_f32 v[40:41], v[44:45], s[36:37], v[32:33] op_sel_hi:[1,0,1]
	v_pk_fma_f32 v[32:33], v[100:101], s[94:95], v[160:161] op_sel_hi:[1,1,0] neg_lo:[0,0,1] neg_hi:[0,0,1]
	v_pk_fma_f32 v[44:45], v[62:63], s[36:37], v[162:163] op_sel_hi:[1,0,1]
	v_pk_fma_f32 v[32:33], v[46:47], s[36:37], v[32:33] op_sel_hi:[1,0,1]
	s_cbranch_vccnz .LBB0_186
; DEV void att_tile64(AttAcc& A, const f32x16& s0, const f32x16& s1, float qs, float slope2, int dt, float lane_bias, bool masked, int wlim,
;                     const bf16_t* vt, size_t vstride) {
;     ...
;   if (masked) {
; #pragma unroll
;     for (int i = 0; i < 32; ++i) {
;       const int c = (i & 7) + 16 * ((i & 15) >> 3) + 32 * (i >> 4);
;       const int di = dt - c;
;       sc[i] = (di >= 0 && di < wlim) ? sc[i] : -3.0e38f;
;     }
;   }
	v_add_u32_e32 v46, -1, v157
	v_cmp_gt_u32_e32 vcc, s61, v46
	v_add_u32_e32 v46, -3, v157
	v_add_u32_e32 v47, -2, v157
	v_cndmask_b32_e32 v119, v219, v119, vcc
	v_cmp_gt_u32_e32 vcc, s60, v157
	s_nop 1
	v_cndmask_b32_e32 v118, v219, v118, vcc
	v_cmp_gt_u32_e32 vcc, s61, v46
	v_add_u32_e32 v46, -5, v157
	s_nop 0
	v_cndmask_b32_e32 v121, v219, v121, vcc
	v_cmp_gt_u32_e32 vcc, s60, v47
	v_add_u32_e32 v47, -4, v157
	s_nop 0
	v_cndmask_b32_e32 v120, v219, v120, vcc
	v_cmp_gt_u32_e32 vcc, s61, v46
	v_add_u32_e32 v46, -7, v157
	s_nop 0
	v_cndmask_b32_e32 v53, v219, v53, vcc
	v_cmp_gt_u32_e32 vcc, s60, v47
	v_add_u32_e32 v47, -6, v157
	s_nop 0
	v_cndmask_b32_e32 v52, v219, v52, vcc
	v_cmp_gt_u32_e32 vcc, s61, v46
	v_add_u32_e32 v46, -16, v157
	s_nop 0
	v_cndmask_b32_e32 v55, v219, v55, vcc
	v_cmp_gt_u32_e32 vcc, s60, v47
	v_subrev_u32_e32 v47, 17, v157
	s_nop 0
	v_cndmask_b32_e32 v54, v219, v54, vcc
	v_cmp_gt_u32_e32 vcc, s61, v47
	v_subrev_u32_e32 v47, 18, v157
	s_nop 0
	v_cndmask_b32_e32 v57, v219, v57, vcc
	v_cmp_gt_u32_e32 vcc, s60, v46
	v_subrev_u32_e32 v46, 19, v157
	s_nop 0
	v_cndmask_b32_e32 v56, v219, v56, vcc
	v_cmp_gt_u32_e32 vcc, s61, v46
	v_subrev_u32_e32 v46, 21, v157
	s_nop 0
	v_cndmask_b32_e32 v59, v219, v59, vcc
	v_cmp_gt_u32_e32 vcc, s60, v47
	v_subrev_u32_e32 v47, 20, v157
	s_nop 0
	v_cndmask_b32_e32 v58, v219, v58, vcc
	v_cmp_gt_u32_e32 vcc, s61, v46
	v_subrev_u32_e32 v46, 23, v157
	s_nop 0
	v_cndmask_b32_e32 v43, v219, v43, vcc
	v_cmp_gt_u32_e32 vcc, s60, v47
	v_subrev_u32_e32 v47, 22, v157
	s_nop 0
	v_cndmask_b32_e32 v42, v219, v42, vcc
	v_cmp_gt_u32_e32 vcc, s61, v46
	v_subrev_u32_e32 v46, 33, v157
	s_nop 0
	v_cndmask_b32_e32 v45, v219, v45, vcc
	v_cmp_gt_u32_e32 vcc, s60, v47
	v_subrev_u32_e32 v47, 32, v157
	s_nop 0
	v_cndmask_b32_e32 v44, v219, v44, vcc
	v_cmp_gt_u32_e32 vcc, s61, v46
	v_subrev_u32_e32 v46, 35, v157
	s_nop 0
	v_cndmask_b32_e32 v117, v219, v117, vcc
	v_cmp_gt_u32_e32 vcc, s60, v47
	v_subrev_u32_e32 v47, 34, v157
	s_nop 0
	v_cndmask_b32_e32 v116, v219, v116, vcc
	v_cmp_gt_u32_e32 vcc, s61, v46
	v_subrev_u32_e32 v46, 37, v157
	s_nop 0
	v_cndmask_b32_e32 v51, v219, v51, vcc
	v_cmp_gt_u32_e32 vcc, s60, v47
	v_subrev_u32_e32 v47, 36, v157
	s_nop 0
	v_cndmask_b32_e32 v50, v219, v50, vcc
	v_cmp_gt_u32_e32 vcc, s61, v46
	v_subrev_u32_e32 v46, 39, v157
	s_nop 0
	v_cndmask_b32_e32 v49, v219, v49, vcc
	v_cmp_gt_u32_e32 vcc, s60, v47
	v_subrev_u32_e32 v47, 38, v157
	s_nop 0
	v_cndmask_b32_e32 v48, v219, v48, vcc
	v_cmp_gt_u32_e32 vcc, s61, v46
	v_subrev_u32_e32 v46, 49, v157
	s_nop 0
	v_cndmask_b32_e32 v35, v219, v35, vcc
	v_cmp_gt_u32_e32 vcc, s60, v47
	v_subrev_u32_e32 v47, 48, v157
	s_nop 0
	v_cndmask_b32_e32 v34, v219, v34, vcc
	v_cmp_gt_u32_e32 vcc, s61, v46
	v_subrev_u32_e32 v46, 51, v157
	s_nop 0
	v_cndmask_b32_e32 v37, v219, v37, vcc
	v_cmp_gt_u32_e32 vcc, s60, v47
	v_subrev_u32_e32 v47, 50, v157
	s_nop 0
	v_cndmask_b32_e32 v36, v219, v36, vcc
	v_cmp_gt_u32_e32 vcc, s61, v46
	v_subrev_u32_e32 v46, 53, v157
	s_nop 0
	v_cndmask_b32_e32 v39, v219, v39, vcc
	v_cmp_gt_u32_e32 vcc, s60, v47
	v_subrev_u32_e32 v47, 52, v157
	s_nop 0
	v_cndmask_b32_e32 v38, v219, v38, vcc
	v_cmp_gt_u32_e32 vcc, s61, v46
	v_subrev_u32_e32 v46, 55, v157
	s_nop 0
	v_cndmask_b32_e32 v41, v219, v41, vcc
	v_cmp_gt_u32_e32 vcc, s60, v47
	v_subrev_u32_e32 v47, 54, v157
	s_nop 0
	v_cndmask_b32_e32 v40, v219, v40, vcc
	v_cmp_gt_u32_e32 vcc, s61, v46
	s_nop 1
	v_cndmask_b32_e32 v33, v219, v33, vcc
	v_cmp_gt_u32_e32 vcc, s60, v47
	s_nop 1
	v_cndmask_b32_e32 v32, v219, v32, vcc

; DEV f32x16 mfma32(bf16x8 a, bf16x8 b, f32x16 c) { return __builtin_amdgcn_mfma_f32_32x32x16_bf16(a, b, c, 0, 0, 0); }
; DEV void pv_tile(f32x16& o0, f32x16& o1, const bf16_t* vt, size_t vstride, const float* p) {
;   const bf16x8 pf0 = pack8(p), pf1 = pack8(p + 8);
;   const bf16x8 a00 = *(const bf16x8*)(vt), a01 = *(const bf16x8*)(vt + 16);
;   const bf16x8 a10 = *(const bf16x8*)(vt + 32 * vstride), a11 = *(const bf16x8*)(vt + 32 * vstride + 16);
;   o0 = mfma32(a00, pf0, o0); o0 = mfma32(a01, pf1, o0);
;   o1 = mfma32(a10, pf0, o1); o1 = mfma32(a11, pf1, o1);
; }
; DEV void att_tile64(AttAcc& A, const f32x16& s0, const f32x16& s1, float qs, float slope2, int dt, float lane_bias, bool masked, int wlim,
;                     const bf16_t* vt, size_t vstride) {
;     ...
;   float p[32]; float ps = 0.f;
; #pragma unroll
;   for (int i = 0; i < 32; ++i) { p[i] = __builtin_amdgcn_exp2f(sc[i] - A.m); ps += p[i]; }
;   A.l += ps;
;   pv_tile(A.o0, A.o1, vt, vstride, p);
;   pv_tile(A.o0, A.o1, vt + 32, vstride, p + 16);
.LBB0_188:
	v_pk_add_f32 v[46:47], v[118:119], v[158:159] op_sel_hi:[1,0] neg_lo:[0,1] neg_hi:[0,1]
	v_pk_add_f32 v[62:63], v[116:117], v[158:159] op_sel_hi:[1,0] neg_lo:[0,1] neg_hi:[0,1]
	ds_read_b128 v[116:119], v159 offset:44032
	ds_read_b128 v[164:167], v159 offset:44064
	v_pk_add_f32 v[60:61], v[120:121], v[158:159] op_sel_hi:[1,0] neg_lo:[0,1] neg_hi:[0,1]
	v_pk_add_f32 v[52:53], v[52:53], v[158:159] op_sel_hi:[1,0] neg_lo:[0,1] neg_hi:[0,1]
	v_pk_add_f32 v[54:55], v[54:55], v[158:159] op_sel_hi:[1,0] neg_lo:[0,1] neg_hi:[0,1]
	v_exp_f32_e32 v46, v46
	v_exp_f32_e32 v47, v47
	v_exp_f32_e32 v60, v60
	v_exp_f32_e32 v61, v61
	v_exp_f32_e32 v52, v52
	v_exp_f32_e32 v53, v53
	v_exp_f32_e32 v54, v54
	v_exp_f32_e32 v55, v55
	v_cvt_pk_bf16_f32 v160, v46, v47
	v_cvt_pk_bf16_f32 v161, v60, v61
	v_cvt_pk_bf16_f32 v162, v52, v53
	v_cvt_pk_bf16_f32 v163, v54, v55
	ds_read_b128 v[168:171], v159 offset:48640
	v_pk_add_f32 v[56:57], v[56:57], v[158:159] op_sel_hi:[1,0] neg_lo:[0,1] neg_hi:[0,1]
	s_waitcnt lgkmcnt(2)
	v_mfma_f32_32x32x16_bf16 v[0:15], v[116:119], v[160:163], v[0:15]
	v_pk_add_f32 v[58:59], v[58:59], v[158:159] op_sel_hi:[1,0] neg_lo:[0,1] neg_hi:[0,1]
	v_pk_add_f32 v[42:43], v[42:43], v[158:159] op_sel_hi:[1,0] neg_lo:[0,1] neg_hi:[0,1]
	v_pk_add_f32 v[44:45], v[44:45], v[158:159] op_sel_hi:[1,0] neg_lo:[0,1] neg_hi:[0,1]
	v_exp_f32_e32 v56, v56
	v_exp_f32_e32 v57, v57
	v_exp_f32_e32 v58, v58
	v_exp_f32_e32 v59, v59
	v_exp_f32_e32 v42, v42
	v_exp_f32_e32 v43, v43
	v_exp_f32_e32 v44, v44
	v_exp_f32_e32 v45, v45
	v_cvt_pk_bf16_f32 v116, v56, v57
	v_cvt_pk_bf16_f32 v117, v58, v59
	v_cvt_pk_bf16_f32 v118, v42, v43
	v_cvt_pk_bf16_f32 v119, v44, v45
	v_pk_add_f32 v[50:51], v[50:51], v[158:159] op_sel_hi:[1,0] neg_lo:[0,1] neg_hi:[0,1]
	s_waitcnt lgkmcnt(1)
	v_mfma_f32_32x32x16_bf16 v[0:15], v[164:167], v[116:119], v[0:15]
	ds_read_b128 v[164:167], v159 offset:48672
	v_pk_add_f32 v[48:49], v[48:49], v[158:159] op_sel_hi:[1,0] neg_lo:[0,1] neg_hi:[0,1]
	v_pk_add_f32 v[34:35], v[34:35], v[158:159] op_sel_hi:[1,0] neg_lo:[0,1] neg_hi:[0,1]
	v_exp_f32_e32 v62, v62
	v_exp_f32_e32 v63, v63
	s_waitcnt lgkmcnt(1)
	v_mfma_f32_32x32x16_bf16 v[16:31], v[168:171], v[160:163], v[16:31]
	ds_read_b128 v[160:163], v159 offset:44096
	v_exp_f32_e32 v50, v50
	v_exp_f32_e32 v51, v51
	v_exp_f32_e32 v48, v48
	v_exp_f32_e32 v49, v49
	v_exp_f32_e32 v34, v34
	v_exp_f32_e32 v35, v35
	s_waitcnt lgkmcnt(1)
	v_mfma_f32_32x32x16_bf16 v[16:31], v[164:167], v[116:119], v[16:31]
	v_cvt_pk_bf16_f32 v116, v62, v63
	v_cvt_pk_bf16_f32 v117, v50, v51
	v_cvt_pk_bf16_f32 v118, v48, v49
	v_cvt_pk_bf16_f32 v119, v34, v35
	ds_read_b128 v[164:167], v159 offset:44128
	v_pk_add_f32 v[36:37], v[36:37], v[158:159] op_sel_hi:[1,0] neg_lo:[0,1] neg_hi:[0,1]
	s_waitcnt lgkmcnt(1)
	v_mfma_f32_32x32x16_bf16 v[0:15], v[160:163], v[116:119], v[0:15]
	v_pk_add_f32 v[38:39], v[38:39], v[158:159] op_sel_hi:[1,0] neg_lo:[0,1] neg_hi:[0,1]
	v_pk_add_f32 v[40:41], v[40:41], v[158:159] op_sel_hi:[1,0] neg_lo:[0,1] neg_hi:[0,1]
	v_pk_add_f32 v[32:33], v[32:33], v[158:159] op_sel_hi:[1,0] neg_lo:[0,1] neg_hi:[0,1]
	v_exp_f32_e32 v36, v36
	v_exp_f32_e32 v37, v37
	v_exp_f32_e32 v38, v38
	v_exp_f32_e32 v39, v39
	v_exp_f32_e32 v40, v40
	v_exp_f32_e32 v41, v41
	v_exp_f32_e32 v32, v32
	v_exp_f32_e32 v33, v33
	v_cvt_pk_bf16_f32 v160, v36, v37
	v_cvt_pk_bf16_f32 v161, v38, v39
	v_cvt_pk_bf16_f32 v162, v40, v41
	v_cvt_pk_bf16_f32 v163, v32, v33
	s_add_i32 s2, s2, 1
	s_andn2_b64 vcc, exec, s[46:47]
	s_waitcnt lgkmcnt(0)
	v_mfma_f32_32x32x16_bf16 v[0:15], v[164:167], v[160:163], v[0:15]
	ds_read_b128 v[164:167], v159 offset:48704
	ds_read_b128 v[168:171], v159 offset:48736
	s_waitcnt lgkmcnt(1)
	v_mfma_f32_32x32x16_bf16 v[16:31], v[164:167], v[116:119], v[16:31]
	s_waitcnt lgkmcnt(0)
	v_mfma_f32_32x32x16_bf16 v[16:31], v[168:171], v[160:163], v[16:31]
	s_cbranch_vccnz .LBB0_181
	s_bitcmp1_b32 s2, 0
	s_cselect_b32 s39, 0x4800, 0
	v_lshl_add_u32 v117, v151, 1, s39
	v_lshl_add_u32 v116, v106, 1, s39
	s_waitcnt vmcnt(3)
	ds_write_b128 v117, v[80:83] offset:34816
	s_waitcnt vmcnt(2)
	ds_write_b128 v117, v[84:87] offset:39424
	s_waitcnt vmcnt(1)
	ds_write_b128 v116, v[88:91] offset:44032
	s_waitcnt vmcnt(0)
	ds_write_b128 v116, v[92:95] offset:48640
	s_branch .LBB0_181
